# attention A loop: bias-tuple validity tracked in an SGPR (no per-step VALU compare), cross-half row-max combine only on the rescale path, LDS waits merged per MFMA pair
# baseline (speedup 1.0000x reference)
; #define FLAS __attribute__((address_space(3)))
; #define FA_SB() __builtin_amdgcn_sched_barrier(0)
; __device__ __forceinline__ float xhalf_max(float m) { unsigned a = __builtin_bit_cast(unsigned, m), b = a; xswap(a, b); return __builtin_fmaxf(__builtin_bit_cast(float, a), __builtin_bit_cast(float, b)); }
; __device__ __forceinline__ void attn_unit_a(FLAS unsigned char* lds, const Unit u) {
;     ...
;     f32x16 pa0, pa1, pb0, pb1; float cbC = 0.f;
;     { bool zi; FA_BIAS(0, pa0, pa1, cbC, zi); if (zi) { pa0 = z16; pa1 = z16; }
;       const FLAS unsigned char* kb = lds + LA_K;
; #pragma unroll
;       for (int d0 = 0; d0 < 4; ++d0) { const int ko = (2 * d0 + hi) * 1024 + ((r32 ^ (2 * d0 + hi)) * 16); const bf16x8 a0 = *(const FLAS bf16x8*)(kb + ko), a1 = *(const FLAS bf16x8*)(kb + ko + 512);
;           pa0 = __builtin_amdgcn_mfma_f32_32x32x16_bf16(a0, qr[d0], pa0, 0, 0, 0); pa1 = __builtin_amdgcn_mfma_f32_32x32x16_bf16(a1, qr[d0], pa1, 0, 0, 0); } }
;     u32x4 pwa[4] = {{0u,0u,0u,0u},{0u,0u,0u,0u},{0u,0u,0u,0u},{0u,0u,0u,0u}}, pwb[4] = {{0u,0u,0u,0u},{0u,0u,0u,0u},{0u,0u,0u,0u},{0u,0u,0u,0u}};
;     ...
;         rm = xhalf_max(rm);
;         FA_SB();
;         if (first || __any(rm > 8.0f)) {
;             const float dl = __builtin_fmaxf(rm, first ? -1000.0f : 0.0f); const float f = first ? 1.0f : __builtin_amdgcn_exp2f(-dl);
;             mrun = first ? dl : mrun + dl; lsum *= f; fpend = f; pend = !first; first = false;
; #pragma unroll
;             for (int r = 0; r < 16; ++r) { pC0[r] = pC0[r] - dl; pC1[r] = pC1[r] - dl; }
;         }
.Lprio_skip:
	s_waitcnt lgkmcnt(0)
	v_readlane_b32 s100, v254, 47
	v_mov_b32_e32 v92, s13
	s_nop 3
	v_mov_b32_e32 v93, s100
	ds_read_b32 v92, v92
	ds_read_b32 v93, v93
	v_sub_f32_e32 v94, v204, v211
	v_add_f32_e32 v96, v128, v94
	v_add_f32_e32 v112, v144, v94
	v_add_f32_e32 v97, v129, v94
	v_add_f32_e32 v113, v145, v94
	v_add_f32_e32 v98, v130, v94
	v_add_f32_e32 v114, v146, v94
	v_add_f32_e32 v99, v131, v94
	v_add_f32_e32 v115, v147, v94
	v_add_f32_e32 v100, v132, v94
	v_add_f32_e32 v116, v148, v94
	v_add_f32_e32 v101, v133, v94
	v_add_f32_e32 v117, v149, v94
	v_add_f32_e32 v102, v134, v94
	v_add_f32_e32 v118, v150, v94
	v_add_f32_e32 v103, v135, v94
	v_add_f32_e32 v119, v151, v94
	v_add_f32_e32 v104, v136, v94
	v_add_f32_e32 v120, v152, v94
	v_add_f32_e32 v105, v137, v94
	v_add_f32_e32 v121, v153, v94
	v_add_f32_e32 v106, v138, v94
	v_add_f32_e32 v122, v154, v94
	v_add_f32_e32 v107, v139, v94
	v_add_f32_e32 v123, v155, v94
	v_add_f32_e32 v108, v140, v94
	v_add_f32_e32 v124, v156, v94
	v_add_f32_e32 v109, v141, v94
	v_add_f32_e32 v125, v157, v94
	v_add_f32_e32 v110, v142, v94
	v_add_f32_e32 v126, v158, v94
	v_add_f32_e32 v111, v143, v94
	v_add_f32_e32 v127, v159, v94
	v_mov_b32_e32 v144, 0x7fc00000
	v_mov_b32_e32 v145, 0x7fc00000
	v_mov_b32_e32 v146, 0x7fc00000
	v_mov_b32_e32 v147, 0x7fc00000
	v_mov_b32_e32 v148, 0x7fc00000
	v_mov_b32_e32 v149, 0x7fc00000
	v_mov_b32_e32 v150, 0x7fc00000
	v_mov_b32_e32 v151, 0x7fc00000
	v_mov_b32_e32 v152, 0x7fc00000
	v_mov_b32_e32 v153, 0x7fc00000
	v_mov_b32_e32 v154, 0x7fc00000
	v_mov_b32_e32 v155, 0x7fc00000
	v_mov_b32_e32 v156, 0x7fc00000
	v_mov_b32_e32 v157, 0x7fc00000
	v_mov_b32_e32 v158, 0x7fc00000
	v_mov_b32_e32 v159, 0x7fc00000
	v_mov_b32_e32 v204, 0
	v_mov_b32_e32 v205, 0
	v_mov_b32_e32 v206, 0
	v_mov_b32_e32 v207, 0
	s_waitcnt lgkmcnt(0)
	v_readfirstlane_b32 s101, v92
	v_readfirstlane_b32 s100, v93
	v_mov_b32_e32 v72, 0
	v_mov_b32_e32 v73, 0
	v_mov_b32_e32 v74, 0
	v_mov_b32_e32 v75, 0
	v_mov_b32_e32 v76, 0
	v_mov_b32_e32 v77, 0
	v_mov_b32_e32 v78, 0
	v_mov_b32_e32 v79, 0
	v_mov_b32_e32 v80, 0
	v_mov_b32_e32 v81, 0
	v_mov_b32_e32 v82, 0
	v_mov_b32_e32 v83, 0
	v_mov_b32_e32 v84, 0
	v_mov_b32_e32 v85, 0
	v_mov_b32_e32 v86, 0
	v_mov_b32_e32 v87, 0
	v_mov_b32_e32 v88, 0
	v_mov_b32_e32 v89, 0
	v_mov_b32_e32 v90, 0
	v_mov_b32_e32 v91, 0
	v_mov_b32_e32 v92, 0
	v_mov_b32_e32 v93, 0
	v_mov_b32_e32 v94, 0
	v_mov_b32_e32 v95, 0
	s_mov_b32 s99, 0x7fc00000
	s_add_i32 s12, s19, -1
	s_and_b32 s18, s12, 3
	s_mulk_i32 s18, 0x4800
	s_cmp_lg_u32 s49, 0
	s_cselect_b32 s12, s18, 0
	v_add_u32_e32 v200, s12, v251
	ds_read_b128 v[128:131], v200 offset:16384
	ds_read_b128 v[132:135], v200 offset:20992
	ds_read_b128 v[136:139], v200 offset:25600
	s_cbranch_execnz .LBB0_435
	s_branch .LBB0_434
.LBB0_440:
	v_mov_b32_e32 v141, v140
	s_nop 1
	v_permlane32_swap_b32 v140, v141
	s_nop 1
	s_nop 0
	v_max_f32_e32 v140, v140, v141
	v_bfrev_b32_e32 v141, 1
	s_mov_b32 s12, 0xc47a0000
	s_branch .LBB0_441
.Lresc_e:
	v_mov_b32_e32 v141, v140
	s_nop 1
	v_permlane32_swap_b32 v140, v141
	s_nop 1
	s_nop 0
	v_max_f32_e32 v140, v140, v141
	s_mov_b32 s12, 0
	v_mov_b32_e32 v141, v211
.LBB0_441:
	s_mov_b32 s99, 0x7fc00000
	v_max_f32_e64 v142, s12, s12
	v_max_f32_e32 v140, v140, v140
	v_max_f32_e32 v140, v140, v142
	v_exp_f32_e64 v142, -v140
	v_add_f32_e32 v211, v141, v140
	v_sub_f32_e32 v111, v111, v140
	v_sub_f32_e32 v110, v110, v140
	v_cndmask_b32_e64 v226, v142, 1.0, s[24:25]
	v_mul_f32_e32 v212, v212, v226
	v_sub_f32_e32 v109, v109, v140
	v_sub_f32_e32 v108, v108, v140
	v_sub_f32_e32 v107, v107, v140
	v_sub_f32_e32 v106, v106, v140
	v_sub_f32_e32 v105, v105, v140
	v_sub_f32_e32 v104, v104, v140
	v_sub_f32_e32 v103, v103, v140
	v_sub_f32_e32 v102, v102, v140
	v_sub_f32_e32 v101, v101, v140
	v_sub_f32_e32 v100, v100, v140
	v_sub_f32_e32 v99, v99, v140
	v_sub_f32_e32 v98, v98, v140
	v_sub_f32_e32 v97, v97, v140
	v_sub_f32_e32 v96, v96, v140
	v_sub_f32_e32 v127, v127, v140
	v_sub_f32_e32 v126, v126, v140
	v_sub_f32_e32 v125, v125, v140
	v_sub_f32_e32 v124, v124, v140
	v_sub_f32_e32 v123, v123, v140
	v_sub_f32_e32 v122, v122, v140
	v_sub_f32_e32 v121, v121, v140
	v_sub_f32_e32 v120, v120, v140
	v_sub_f32_e32 v119, v119, v140
	v_sub_f32_e32 v118, v118, v140
	v_sub_f32_e32 v117, v117, v140
	v_sub_f32_e32 v116, v116, v140
	v_sub_f32_e32 v115, v115, v140
	v_sub_f32_e32 v114, v114, v140
	v_sub_f32_e32 v113, v113, v140
	v_sub_f32_e32 v112, v112, v140
	s_branch .LBB0_442

; #define FA_SB() __builtin_amdgcn_sched_barrier(0)
; #define FA_EXP2(J, PX, R) do { const float e0_ = __builtin_amdgcn_exp2f(PX[R]), e1_ = __builtin_amdgcn_exp2f(PX[(R) + 1]); ps += e0_; ps += e1_; PWN[(J) >> 2][(J) & 3] = cvtpk(e0_, e1_); } while (0)
; __device__ __forceinline__ void attn_unit_a(FLAS unsigned char* lds, const Unit u) {
;     ...
;         float cbN; bool ziN; const int inx = (i + 1 < NT) ? i + 1 : NT - 1;
;         FA_BIAS(inx, pN0, pN1, cbN, ziN);
;         FA_SB();
;         if (ziN) { pN0 = __builtin_amdgcn_mfma_f32_32x32x16_bf16(kf[0], qr[0], z16, 0, 0, 0); FA_EXP2(8, pC1, 0); FA_SB(); pN1 = __builtin_amdgcn_mfma_f32_32x32x16_bf16(kf[1], qr[0], z16, 0, 0, 0); }
.Lz_upd_e:
	v_sub_f32_e32 v142, s98, v211
	s_mov_b32 s99, s98
	v_mov_b32_e32 v144, v142
	v_mov_b32_e32 v145, v142
	v_mov_b32_e32 v146, v142
	v_mov_b32_e32 v147, v142
	v_mov_b32_e32 v148, v142
	v_mov_b32_e32 v149, v142
	v_mov_b32_e32 v150, v142
	v_mov_b32_e32 v151, v142
	v_mov_b32_e32 v152, v142
	v_mov_b32_e32 v153, v142
	v_mov_b32_e32 v154, v142
	v_mov_b32_e32 v155, v142
	v_mov_b32_e32 v156, v142
	v_mov_b32_e32 v157, v142
	v_mov_b32_e32 v158, v142
	v_mov_b32_e32 v159, v142
	s_nop 1
	s_branch .Lz_go_e

; #define FA_SB() __builtin_amdgcn_sched_barrier(0)
; __device__ __forceinline__ float xhalf_max(float m) { unsigned a = __builtin_bit_cast(unsigned, m), b = a; xswap(a, b); return __builtin_fmaxf(__builtin_bit_cast(float, a), __builtin_bit_cast(float, b)); }
; #define FA_EXP2(J, PX, R) do { const float e0_ = __builtin_amdgcn_exp2f(PX[R]), e1_ = __builtin_amdgcn_exp2f(PX[(R) + 1]); ps += e0_; ps += e1_; PWN[(J) >> 2][(J) & 3] = cvtpk(e0_, e1_); } while (0)
; __device__ __forceinline__ void attn_unit_a(FLAS unsigned char* lds, const Unit u) {
;     ...
;         rm = xhalf_max(rm);
;         FA_SB();
;         if (first || __any(rm > 8.0f)) {
;             const float dl = __builtin_fmaxf(rm, first ? -1000.0f : 0.0f); const float f = first ? 1.0f : __builtin_amdgcn_exp2f(-dl);
;             mrun = first ? dl : mrun + dl; lsum *= f; fpend = f; pend = !first; first = false;
; #pragma unroll
;             for (int r = 0; r < 16; ++r) { pC0[r] = pC0[r] - dl; pC1[r] = pC1[r] - dl; }
;         }
;     ...
;         float cbN; bool ziN; const int inx = (i + 1 < NT) ? i + 1 : NT - 1;
;         FA_BIAS(inx, pN0, pN1, cbN, ziN);
;         FA_SB();
;         if (ziN) { pN0 = __builtin_amdgcn_mfma_f32_32x32x16_bf16(kf[0], qr[0], z16, 0, 0, 0); FA_EXP2(8, pC1, 0); FA_SB(); pN1 = __builtin_amdgcn_mfma_f32_32x32x16_bf16(kf[1], qr[0], z16, 0, 0, 0); }
.Lresc_o:
	v_mov_b32_e32 v97, v96
	s_nop 1
	v_permlane32_swap_b32 v96, v97
	s_nop 1
	s_nop 0
	v_max_f32_e32 v96, v96, v97
	s_mov_b32 s99, 0x7fc00000
	s_mov_b64 s[0:1], -1
	v_max_f32_e32 v96, v96, v96
	v_max_f32_e32 v96, 0, v96
	v_exp_f32_e64 v226, -v96
	v_add_f32_e32 v211, v211, v96
	v_sub_f32_e32 v64, v64, v96
	v_sub_f32_e32 v65, v65, v96
	v_mul_f32_e32 v212, v212, v226
	v_sub_f32_e32 v66, v66, v96
	v_sub_f32_e32 v67, v67, v96
	v_sub_f32_e32 v68, v68, v96
	v_sub_f32_e32 v69, v69, v96
	v_sub_f32_e32 v70, v70, v96
	v_sub_f32_e32 v71, v71, v96
	v_sub_f32_e32 v72, v72, v96
	v_sub_f32_e32 v73, v73, v96
	v_sub_f32_e32 v74, v74, v96
	v_sub_f32_e32 v75, v75, v96
	v_sub_f32_e32 v76, v76, v96
	v_sub_f32_e32 v77, v77, v96
	v_sub_f32_e32 v78, v78, v96
	v_sub_f32_e32 v79, v79, v96
	v_sub_f32_e32 v80, v80, v96
	v_sub_f32_e32 v81, v81, v96
	v_sub_f32_e32 v82, v82, v96
	v_sub_f32_e32 v83, v83, v96
	v_sub_f32_e32 v84, v84, v96
	v_sub_f32_e32 v85, v85, v96
	v_sub_f32_e32 v86, v86, v96
	v_sub_f32_e32 v87, v87, v96
	v_sub_f32_e32 v88, v88, v96
	v_sub_f32_e32 v89, v89, v96
	v_sub_f32_e32 v90, v90, v96
	v_sub_f32_e32 v91, v91, v96
	v_sub_f32_e32 v92, v92, v96
	v_sub_f32_e32 v93, v93, v96
	v_sub_f32_e32 v94, v94, v96
	v_sub_f32_e32 v95, v95, v96
	s_branch .LBB0_462
.Lz_upd_o:
	v_sub_f32_e32 v126, s98, v211
	s_mov_b32 s99, s98
	v_mov_b32_e32 v144, v126
	v_mov_b32_e32 v145, v126
	v_mov_b32_e32 v146, v126
	v_mov_b32_e32 v147, v126
	v_mov_b32_e32 v148, v126
	v_mov_b32_e32 v149, v126
	v_mov_b32_e32 v150, v126
	v_mov_b32_e32 v151, v126
	v_mov_b32_e32 v152, v126
	v_mov_b32_e32 v153, v126
	v_mov_b32_e32 v154, v126
	v_mov_b32_e32 v155, v126
	v_mov_b32_e32 v156, v126
	v_mov_b32_e32 v157, v126
	v_mov_b32_e32 v158, v126
	v_mov_b32_e32 v159, v126
	s_nop 1
	s_branch .Lz_go_o

; #define FLAS __attribute__((address_space(3)))
; __device__ __forceinline__ void attn_unit_a(FLAS unsigned char* lds, const Unit u) {
;     ...
;         if (i + 2 < NT) { kreg = *(const u32x4*)(ksrc + (size_t)(u.t_lo + i + 2) * 64 * u.ldk);
; #pragma unroll
;             for (int j = 0; j < 2; ++j) vreg[j] = *(const u32x4*)(vsrc + (size_t)j * 64 * MTOK + (u.t_lo + i + 2) * 64); }
;         const int vsp = (i == 0) ? 0 : ((i - 1) & 3);
;         const FLAS unsigned char* vb_ = lds + LA_V + vsp * VBUF + r32 * VPITCH + hi * 16;
;         const FLAS unsigned char* kb = lds + LA_K + ((i + 1) & 1) * KBUF;
;     ...
;         u32x4 vr[3];
; #pragma unroll
;         for (int m = 0; m < 3; ++m) vr[m] = FA_VFRAG(m);
;         const float off = cbC - mrun;
;         FA_SB();
;         float ra, rb, rm;
;         FA_PVM(0); pC0[0] = fadd_s(pC0[0], off); pC1[0] = fadd_s(pC1[0], off); pC0[1] = fadd_s(pC0[1], off); pC1[1] = fadd_s(pC1[1], off); pC0[2] = fadd_s(pC0[2], off); pC1[2] = fadd_s(pC1[2], off); FA_SB();
;         FA_PVM(1); ra = __builtin_fmaxf(__builtin_fmaxf(pC0[0], pC0[1]), pC0[2]); rb = __builtin_fmaxf(__builtin_fmaxf(pC1[0], pC1[1]), pC1[2]); pC0[3] = fadd_s(pC0[3], off); pC1[3] = fadd_s(pC1[3], off); pC0[4] = fadd_s(pC0[4], off); pC1[4] = fadd_s(pC1[4], off); FA_SB();
;         FA_PVM(2); ra = __builtin_fmaxf(__builtin_fmaxf(ra, pC0[3]), pC0[4]); rb = __builtin_fmaxf(__builtin_fmaxf(rb, pC1[3]), pC1[4]); pC0[5] = fadd_s(pC0[5], off); pC1[5] = fadd_s(pC1[5], off); pC0[6] = fadd_s(pC0[6], off); pC1[6] = fadd_s(pC1[6], off); FA_SB();
;         FA_PVM(3); ra = __builtin_fmaxf(__builtin_fmaxf(ra, pC0[5]), pC0[6]); rb = __builtin_fmaxf(__builtin_fmaxf(rb, pC1[5]), pC1[6]); pC0[7] = fadd_s(pC0[7], off); pC1[7] = fadd_s(pC1[7], off); pC0[8] = fadd_s(pC0[8], off); pC1[8] = fadd_s(pC1[8], off); FA_SB();
;         FA_PVM(4); ra = __builtin_fmaxf(__builtin_fmaxf(ra, pC0[7]), pC0[8]); rb = __builtin_fmaxf(__builtin_fmaxf(rb, pC1[7]), pC1[8]); pC0[9] = fadd_s(pC0[9], off); pC1[9] = fadd_s(pC1[9], off); pC0[10] = fadd_s(pC0[10], off); pC1[10] = fadd_s(pC1[10], off); FA_SB();
;         FA_PVM(5); ra = __builtin_fmaxf(__builtin_fmaxf(ra, pC0[9]), pC0[10]); rb = __builtin_fmaxf(__builtin_fmaxf(rb, pC1[9]), pC1[10]); pC0[11] = fadd_s(pC0[11], off); pC1[11] = fadd_s(pC1[11], off); pC0[12] = fadd_s(pC0[12], off); pC1[12] = fadd_s(pC1[12], off); FA_SB();
.LBB0_435:
	s_cmpk_lt_u32 s19, 0x7e
	s_cselect_b64 s[0:1], -1, 0
	s_cmpk_gt_u32 s19, 0x7d
	s_cselect_b64 s[4:5], -1, 0
	s_xor_b64 s[20:21], s[24:25], -1
	s_waitcnt lgkmcnt(1)
	v_mfma_f32_32x32x16_bf16 v[48:63], v[128:131], v[204:207], v[48:63]
	ds_read_b128 v[128:131], v200 offset:30208
	s_and_b64 vcc, exec, s[4:5]
	v_lshl_add_u64 v[234:235], v[230:231], 0, v[208:209]
	v_lshl_add_u64 v[232:233], v[228:229], 0, v[208:209]
	s_cbranch_vccnz .LBB0_437
	v_add_co_u32_e32 v142, vcc, 0xd660000, v234
	s_nop 1
	v_addc_co_u32_e32 v143, vcc, 0, v235, vcc
	global_load_dwordx4 v[176:179], v[142:143], off
	v_add_co_u32_e32 v142, vcc, 0x13600000, v232
	s_nop 1
	v_addc_co_u32_e32 v143, vcc, 0, v233, vcc
	global_load_dwordx4 v[180:183], v[142:143], off offset:256
	v_add_co_u32_e32 v142, vcc, 0x13a00000, v232
	s_nop 1
	v_addc_co_u32_e32 v143, vcc, 0, v233, vcc
	global_load_dwordx4 v[184:187], v[142:143], off offset:256
.LBB0_437:
	v_max3_f32 v140, v96, v97, v98
	v_max3_f32 v141, v112, v113, v114
	v_cvt_pk_bf16_f32 v196, v72, v73
	v_cvt_pk_bf16_f32 v197, v74, v75
	v_add_f32_e32 v212, v80, v212
	v_add_f32_e32 v212, v81, v212
	v_mfma_f32_32x32x16_bf16 v[32:47], v[132:135], v[204:207], v[32:47]
	ds_read_b128 v[132:135], v200 offset:16416
	v_max3_f32 v140, v140, v99, v100
	v_max3_f32 v141, v141, v115, v116
	v_cvt_pk_bf16_f32 v198, v76, v77
	v_cvt_pk_bf16_f32 v199, v78, v79
	v_add_f32_e32 v212, v82, v212
	v_add_f32_e32 v212, v83, v212
	s_waitcnt lgkmcnt(1)
	v_mfma_f32_32x32x16_bf16 v[16:31], v[136:139], v[204:207], v[16:31]
	ds_read_b128 v[136:139], v200 offset:21024
	v_max3_f32 v140, v140, v101, v102
	v_max3_f32 v141, v141, v117, v118
	v_cvt_pk_bf16_f32 v192, v80, v81
	v_cvt_pk_bf16_f32 v193, v82, v83
	v_add_f32_e32 v212, v84, v212
	v_add_f32_e32 v212, v85, v212
	v_mfma_f32_32x32x16_bf16 v[0:15], v[128:131], v[204:207], v[0:15]
	ds_read_b128 v[128:131], v200 offset:25632
	v_max3_f32 v140, v140, v103, v104
	v_max3_f32 v141, v141, v119, v120
	v_cvt_pk_bf16_f32 v194, v84, v85
	v_cvt_pk_bf16_f32 v195, v86, v87
	v_add_f32_e32 v212, v86, v212
	v_add_f32_e32 v212, v87, v212
	s_waitcnt lgkmcnt(1)
	v_mfma_f32_32x32x16_bf16 v[48:63], v[132:135], v[196:199], v[48:63]
	ds_read_b128 v[132:135], v200 offset:30240
	v_max3_f32 v140, v140, v105, v106
	v_max3_f32 v141, v141, v121, v122
	v_cvt_pk_bf16_f32 v188, v88, v89
	v_cvt_pk_bf16_f32 v189, v90, v91
	v_add_f32_e32 v212, v88, v212
	v_add_f32_e32 v212, v89, v212
	v_mfma_f32_32x32x16_bf16 v[32:47], v[136:139], v[196:199], v[32:47]
	ds_read_b128 v[136:139], v200 offset:16448
	v_max3_f32 v140, v140, v107, v108
	v_max3_f32 v141, v141, v123, v124
	v_cvt_pk_bf16_f32 v190, v92, v93
	v_cvt_pk_bf16_f32 v191, v94, v95
	v_add_f32_e32 v212, v90, v212
	v_add_f32_e32 v212, v91, v212
	s_waitcnt lgkmcnt(1)
	v_mfma_f32_32x32x16_bf16 v[16:31], v[128:131], v[196:199], v[16:31]
	ds_read_b128 v[128:131], v200 offset:21056
	v_max3_f32 v140, v140, v109, v110
	v_max3_f32 v141, v141, v125, v126
	v_add_f32_e32 v212, v92, v212
	v_add_f32_e32 v212, v93, v212
	v_mfma_f32_32x32x16_bf16 v[0:15], v[132:135], v[196:199], v[0:15]
	ds_read_b128 v[132:135], v200 offset:25664
	v_max3_f32 v140, v140, v141, v111
	v_max_f32_e32 v140, v140, v127
	v_add_f32_e32 v212, v94, v212
	v_add_f32_e32 v212, v95, v212
	s_andn2_b64 vcc, exec, s[20:21]
	s_cbranch_vccnz .LBB0_440
	v_cmp_lt_f32_e32 vcc, s39, v140
	s_cbranch_vccnz .Lresc_e
	s_mov_b64 s[20:21], 0
.LBB0_442:
	s_waitcnt lgkmcnt(1)
	v_mfma_f32_32x32x16_bf16 v[48:63], v[136:139], v[192:195], v[48:63]
	ds_read_b128 v[136:139], v200 offset:30272
	v_exp_f32_e32 v96, v96
	v_exp_f32_e32 v97, v97
	v_mfma_f32_32x32x16_bf16 v[32:47], v[128:131], v[192:195], v[32:47]
	ds_read_b128 v[128:131], v200 offset:16480
	v_exp_f32_e32 v98, v98
	v_exp_f32_e32 v99, v99
	v_add_f32_e32 v212, v96, v212
	v_add_f32_e32 v212, v97, v212
	s_waitcnt lgkmcnt(1)
	v_mfma_f32_32x32x16_bf16 v[16:31], v[132:135], v[192:195], v[16:31]
	ds_read_b128 v[132:135], v200 offset:21088
	v_exp_f32_e32 v100, v100
	v_exp_f32_e32 v101, v101
	v_add_f32_e32 v212, v98, v212
	v_add_f32_e32 v212, v99, v212
	v_mfma_f32_32x32x16_bf16 v[0:15], v[136:139], v[192:195], v[0:15]
	ds_read_b128 v[136:139], v200 offset:25696
	v_exp_f32_e32 v102, v102
	v_exp_f32_e32 v103, v103
	v_add_f32_e32 v212, v100, v212
	v_add_f32_e32 v212, v101, v212
	s_waitcnt lgkmcnt(1)
	v_mfma_f32_32x32x16_bf16 v[48:63], v[128:131], v[188:191], v[48:63]
	ds_read_b128 v[128:131], v200 offset:30304
	ds_read_b128 v[204:207], v247 offset:8192
	ds_read_b128 v[200:203], v247 offset:8704
	ds_read_b128 v[196:199], v248 offset:8192
	ds_read_b128 v[192:195], v248 offset:8704
	v_exp_f32_e32 v104, v104
	v_exp_f32_e32 v105, v105
	v_add_f32_e32 v212, v102, v212
	v_add_f32_e32 v212, v103, v212
	v_mfma_f32_32x32x16_bf16 v[32:47], v[132:135], v[188:191], v[32:47]
	v_exp_f32_e32 v106, v106
	v_exp_f32_e32 v107, v107
	v_add_f32_e32 v212, v104, v212
	v_add_f32_e32 v212, v105, v212
	s_waitcnt lgkmcnt(4)
	v_mfma_f32_32x32x16_bf16 v[16:31], v[136:139], v[188:191], v[16:31]
	v_exp_f32_e32 v108, v108
	v_exp_f32_e32 v109, v109
	v_add_f32_e32 v212, v106, v212
	v_add_f32_e32 v212, v107, v212
	v_mfma_f32_32x32x16_bf16 v[0:15], v[128:131], v[188:191], v[0:15]
	v_exp_f32_e32 v110, v110
	v_exp_f32_e32 v111, v111
	v_add_f32_e32 v212, v108, v212
	v_add_f32_e32 v212, v109, v212
	s_sub_i32 s12, s48, 31
	s_cmpk_lt_i32 s12, 0x22f
	s_cselect_b32 s98, s100, s101
	s_cselect_b32 s15, 1, 0
	s_cmpk_gt_i32 s48, 0xfd92
	s_cselect_b32 s15, s15, 0
	s_cmp_lg_u32 s15, 0
	s_cbranch_scc1 .Lgather_e
	s_cmp_lg_u32 s99, s98
	s_cbranch_scc1 .Lz_upd_e

; #define FLAS __attribute__((address_space(3)))
; #define FA_SB() __builtin_amdgcn_sched_barrier(0)
; #define FA_EXP2(J, PX, R) do { const float e0_ = __builtin_amdgcn_exp2f(PX[R]), e1_ = __builtin_amdgcn_exp2f(PX[(R) + 1]); ps += e0_; ps += e1_; PWN[(J) >> 2][(J) & 3] = cvtpk(e0_, e1_); } while (0)
; __device__ __forceinline__ void attn_unit_a(FLAS unsigned char* lds, const Unit u) {
;     ...
;         kf[0] = FA_KF(2, 0); kf[1] = FA_KF(2, 1); FA_EXP2(9, pC1, 2); FA_SB();
;         pN0 = __builtin_amdgcn_mfma_f32_32x32x16_bf16(kf[2], qr[1], pN0, 0, 0, 0); FA_EXP2(10, pC1, 4); FA_SB();
;         pN1 = __builtin_amdgcn_mfma_f32_32x32x16_bf16(kf[3], qr[1], pN1, 0, 0, 0); kf[2] = FA_KF(3, 0); kf[3] = FA_KF(3, 1); FA_EXP2(11, pC1, 6); FA_SB();
;         pN0 = __builtin_amdgcn_mfma_f32_32x32x16_bf16(kf[0], qr[2], pN0, 0, 0, 0); FA_EXP2(12, pC1, 8); FA_SB();
;         pN1 = __builtin_amdgcn_mfma_f32_32x32x16_bf16(kf[1], qr[2], pN1, 0, 0, 0); FA_EXP2(13, pC1, 10); FA_SB();
;         pN0 = __builtin_amdgcn_mfma_f32_32x32x16_bf16(kf[2], qr[3], pN0, 0, 0, 0); FA_EXP2(14, pC1, 12); FA_SB();
;         pN1 = __builtin_amdgcn_mfma_f32_32x32x16_bf16(kf[3], qr[3], pN1, 0, 0, 0); FA_EXP2(15, pC1, 14); FA_SB();
;     ...
;         lsum += ps; cbC = cbN;
;         if (i + 2 < NT) { *(FLAS u32x4*)(lds + LA_K + (i & 1) * KBUF + kdst) = kreg;
; #pragma unroll
;             for (int j = 0; j < 2; ++j) { *(FLAS u32x2*)(lds + LA_V + ((i + 2) & 3) * VBUF + vdst + j * 64 * VPITCH) = (u32x2){vreg[j].x, vreg[j].y}; *(FLAS u32x2*)(lds + LA_V + ((i + 2) & 3) * VBUF + vdst + j * 64 * VPITCH + 16) = (u32x2){vreg[j].z, vreg[j].w}; } }
.Lk2_e:
	ds_read_b128 v[128:131], v249 offset:8192
	ds_read_b128 v[132:135], v249 offset:8704
	s_add_i32 s34, s19, 2
	v_mfma_f32_32x32x16_bf16 v[64:79], v[196:199], v[164:167], v[64:79]
	v_exp_f32_e32 v116, v116
	v_exp_f32_e32 v117, v117
	v_mfma_f32_32x32x16_bf16 v[80:95], v[192:195], v[164:167], v[80:95]
	ds_read_b128 v[136:139], v250 offset:8192
	ds_read_b128 v[140:143], v250 offset:8704
	s_and_b32 s0, s34, 2
	s_mulk_i32 s0, 0x4800
	v_add_u32_e32 v188, s0, v245
	v_add_u32_e32 v189, 0x4000, v188
	v_add_u32_e32 v188, 0x6000, v188
	s_waitcnt vmcnt(2)
	ds_write_b128 v225, v[176:179]
	s_waitcnt vmcnt(1)
	ds_write2_b64 v189, v[180:181], v[182:183] offset1:2
	s_waitcnt vmcnt(0)
	ds_write2_b64 v188, v[184:185], v[186:187] offset0:128 offset1:130
	v_exp_f32_e32 v118, v118
	v_exp_f32_e32 v119, v119
	s_and_b32 s0, s19, 2
	s_mulk_i32 s0, 0x4800
	v_add_u32_e32 v201, s0, v251
	s_waitcnt lgkmcnt(5)
	v_mfma_f32_32x32x16_bf16 v[64:79], v[128:131], v[168:171], v[64:79]
	ds_read_b128 v[128:131], v201 offset:16384
	v_exp_f32_e32 v120, v120
	v_exp_f32_e32 v121, v121
	v_mfma_f32_32x32x16_bf16 v[80:95], v[132:135], v[168:171], v[80:95]
	ds_read_b128 v[132:135], v201 offset:20992
	v_exp_f32_e32 v122, v122
	v_exp_f32_e32 v123, v123
	s_waitcnt lgkmcnt(5)
	v_mfma_f32_32x32x16_bf16 v[64:79], v[136:139], v[172:175], v[64:79]
	ds_read_b128 v[136:139], v201 offset:25600
	v_exp_f32_e32 v124, v124
	v_exp_f32_e32 v125, v125
	v_mfma_f32_32x32x16_bf16 v[80:95], v[140:143], v[172:175], v[80:95]
	v_exp_f32_e32 v126, v126
	v_exp_f32_e32 v127, v127
	v_cvt_pk_bf16_f32 v140, v96, v97
	v_cvt_pk_bf16_f32 v141, v98, v99
	v_cvt_pk_bf16_f32 v142, v100, v101
	v_cvt_pk_bf16_f32 v143, v102, v103

; #define FLAS __attribute__((address_space(3)))
; __device__ __forceinline__ void attn_unit_a(FLAS unsigned char* lds, const Unit u) {
;     ...
;         if (i + 2 < NT) { kreg = *(const u32x4*)(ksrc + (size_t)(u.t_lo + i + 2) * 64 * u.ldk);
; #pragma unroll
;             for (int j = 0; j < 2; ++j) vreg[j] = *(const u32x4*)(vsrc + (size_t)j * 64 * MTOK + (u.t_lo + i + 2) * 64); }
;         const int vsp = (i == 0) ? 0 : ((i - 1) & 3);
;         const FLAS unsigned char* vb_ = lds + LA_V + vsp * VBUF + r32 * VPITCH + hi * 16;
;         const FLAS unsigned char* kb = lds + LA_K + ((i + 1) & 1) * KBUF;
;     ...
;         u32x4 vr[3];
; #pragma unroll
;         for (int m = 0; m < 3; ++m) vr[m] = FA_VFRAG(m);
;         const float off = cbC - mrun;
;         FA_SB();
;         float ra, rb, rm;
;         FA_PVM(0); pC0[0] = fadd_s(pC0[0], off); pC1[0] = fadd_s(pC1[0], off); pC0[1] = fadd_s(pC0[1], off); pC1[1] = fadd_s(pC1[1], off); pC0[2] = fadd_s(pC0[2], off); pC1[2] = fadd_s(pC1[2], off); FA_SB();
;         FA_PVM(1); ra = __builtin_fmaxf(__builtin_fmaxf(pC0[0], pC0[1]), pC0[2]); rb = __builtin_fmaxf(__builtin_fmaxf(pC1[0], pC1[1]), pC1[2]); pC0[3] = fadd_s(pC0[3], off); pC1[3] = fadd_s(pC1[3], off); pC0[4] = fadd_s(pC0[4], off); pC1[4] = fadd_s(pC1[4], off); FA_SB();
;         FA_PVM(2); ra = __builtin_fmaxf(__builtin_fmaxf(ra, pC0[3]), pC0[4]); rb = __builtin_fmaxf(__builtin_fmaxf(rb, pC1[3]), pC1[4]); pC0[5] = fadd_s(pC0[5], off); pC1[5] = fadd_s(pC1[5], off); pC0[6] = fadd_s(pC0[6], off); pC1[6] = fadd_s(pC1[6], off); FA_SB();
;         FA_PVM(3); ra = __builtin_fmaxf(__builtin_fmaxf(ra, pC0[5]), pC0[6]); rb = __builtin_fmaxf(__builtin_fmaxf(rb, pC1[5]), pC1[6]); pC0[7] = fadd_s(pC0[7], off); pC1[7] = fadd_s(pC1[7], off); pC0[8] = fadd_s(pC0[8], off); pC1[8] = fadd_s(pC1[8], off); FA_SB();
;         FA_PVM(4); ra = __builtin_fmaxf(__builtin_fmaxf(ra, pC0[7]), pC0[8]); rb = __builtin_fmaxf(__builtin_fmaxf(rb, pC1[7]), pC1[8]); pC0[9] = fadd_s(pC0[9], off); pC1[9] = fadd_s(pC1[9], off); pC0[10] = fadd_s(pC0[10], off); pC1[10] = fadd_s(pC1[10], off); FA_SB();
;         FA_PVM(5); ra = __builtin_fmaxf(__builtin_fmaxf(ra, pC0[9]), pC0[10]); rb = __builtin_fmaxf(__builtin_fmaxf(rb, pC1[9]), pC1[10]); pC0[11] = fadd_s(pC0[11], off); pC1[11] = fadd_s(pC1[11], off); pC0[12] = fadd_s(pC0[12], off); pC1[12] = fadd_s(pC1[12], off); FA_SB();
.LBB0_458:
	s_cmpk_lt_u32 s19, 0x7d
	s_cselect_b64 s[20:21], -1, 0
	s_waitcnt lgkmcnt(1)
	v_mfma_f32_32x32x16_bf16 v[48:63], v[128:131], v[140:143], v[48:63]
	ds_read_b128 v[128:131], v201 offset:30208
	s_cmpk_gt_u32 s19, 0x7c
	s_cbranch_scc1 .LBB0_460
	v_add_co_u32_e32 v98, vcc, 0xd690000, v234
	s_nop 1
	v_addc_co_u32_e32 v99, vcc, 0, v235, vcc
	global_load_dwordx4 v[176:179], v[98:99], off
	v_add_co_u32_e32 v98, vcc, 0x13600000, v232
	s_nop 1
	v_addc_co_u32_e32 v99, vcc, 0, v233, vcc
	global_load_dwordx4 v[180:183], v[98:99], off offset:384
	v_add_co_u32_e32 v98, vcc, 0x13a00000, v232
	s_nop 1
	v_addc_co_u32_e32 v99, vcc, 0, v233, vcc
	global_load_dwordx4 v[184:187], v[98:99], off offset:384
.LBB0_460:
	v_max3_f32 v96, v64, v65, v66
	v_max3_f32 v97, v80, v81, v82
	v_cvt_pk_bf16_f32 v232, v104, v105
	v_cvt_pk_bf16_f32 v233, v106, v107
	v_add_f32_e32 v212, v112, v212
	v_add_f32_e32 v212, v113, v212
	v_mfma_f32_32x32x16_bf16 v[32:47], v[132:135], v[140:143], v[32:47]
	ds_read_b128 v[132:135], v201 offset:16416
	v_max3_f32 v96, v96, v67, v68
	v_max3_f32 v97, v97, v83, v84
	v_cvt_pk_bf16_f32 v234, v108, v109
	v_cvt_pk_bf16_f32 v235, v110, v111
	v_add_f32_e32 v212, v114, v212
	v_add_f32_e32 v212, v115, v212
	s_waitcnt lgkmcnt(1)
	v_mfma_f32_32x32x16_bf16 v[16:31], v[136:139], v[140:143], v[16:31]
	ds_read_b128 v[136:139], v201 offset:21024
	v_max3_f32 v96, v96, v69, v70
	v_max3_f32 v97, v97, v85, v86
	v_add_f32_e32 v212, v116, v212
	v_add_f32_e32 v212, v117, v212
	v_mfma_f32_32x32x16_bf16 v[0:15], v[128:131], v[140:143], v[0:15]
	ds_read_b128 v[128:131], v201 offset:25632
	v_max3_f32 v96, v96, v71, v72
	v_max3_f32 v97, v97, v87, v88
	v_add_f32_e32 v212, v118, v212
	v_add_f32_e32 v212, v119, v212
	s_waitcnt lgkmcnt(1)
	v_mfma_f32_32x32x16_bf16 v[48:63], v[132:135], v[232:235], v[48:63]
	ds_read_b128 v[132:135], v201 offset:30240
	v_max3_f32 v96, v96, v73, v74
	v_max3_f32 v97, v97, v89, v90
	v_cvt_pk_bf16_f32 v140, v112, v113
	v_cvt_pk_bf16_f32 v141, v114, v115
	v_add_f32_e32 v212, v120, v212
	v_add_f32_e32 v212, v121, v212
	v_mfma_f32_32x32x16_bf16 v[32:47], v[136:139], v[232:235], v[32:47]
	ds_read_b128 v[136:139], v201 offset:16448
	v_max3_f32 v96, v96, v75, v76
	v_max3_f32 v97, v97, v91, v92
	v_cvt_pk_bf16_f32 v142, v116, v117
	v_cvt_pk_bf16_f32 v143, v118, v119
	v_add_f32_e32 v212, v122, v212
	v_add_f32_e32 v212, v123, v212
	s_waitcnt lgkmcnt(1)
	v_mfma_f32_32x32x16_bf16 v[16:31], v[128:131], v[232:235], v[16:31]
	ds_read_b128 v[128:131], v201 offset:21056
	v_max3_f32 v96, v96, v77, v78
	v_max3_f32 v97, v97, v93, v94
	v_add_f32_e32 v212, v124, v212
	v_add_f32_e32 v212, v125, v212
	v_mfma_f32_32x32x16_bf16 v[0:15], v[132:135], v[232:235], v[0:15]
	ds_read_b128 v[132:135], v201 offset:25664
	v_max3_f32 v96, v96, v97, v79
	v_max_f32_e32 v96, v96, v95
	v_add_f32_e32 v212, v126, v212
	v_add_f32_e32 v212, v127, v212
	v_cmp_lt_f32_e32 vcc, s39, v96
	s_mov_b64 s[0:1], 0
	s_cbranch_vccnz .Lresc_o
.LBB0_462:
	s_waitcnt lgkmcnt(1)
	v_mfma_f32_32x32x16_bf16 v[48:63], v[136:139], v[140:143], v[48:63]
	ds_read_b128 v[136:139], v201 offset:30272
	v_exp_f32_e32 v64, v64
	v_exp_f32_e32 v65, v65
	v_cvt_pk_bf16_f32 v232, v120, v121
	v_cvt_pk_bf16_f32 v233, v122, v123
	v_mfma_f32_32x32x16_bf16 v[32:47], v[128:131], v[140:143], v[32:47]
	ds_read_b128 v[128:131], v201 offset:16480
	v_exp_f32_e32 v66, v66
	v_exp_f32_e32 v67, v67
	v_add_f32_e32 v212, v64, v212
	v_add_f32_e32 v212, v65, v212
	v_cvt_pk_bf16_f32 v234, v124, v125
	v_cvt_pk_bf16_f32 v235, v126, v127
	s_waitcnt lgkmcnt(1)
	v_mfma_f32_32x32x16_bf16 v[16:31], v[132:135], v[140:143], v[16:31]
	ds_read_b128 v[132:135], v201 offset:21088
	v_exp_f32_e32 v68, v68
	v_exp_f32_e32 v69, v69
	v_add_f32_e32 v212, v66, v212
	v_add_f32_e32 v212, v67, v212
	v_mfma_f32_32x32x16_bf16 v[0:15], v[136:139], v[140:143], v[0:15]
	ds_read_b128 v[136:139], v201 offset:25696
	v_exp_f32_e32 v70, v70
	v_exp_f32_e32 v71, v71
	v_add_f32_e32 v212, v68, v212
	v_add_f32_e32 v212, v69, v212
	s_waitcnt lgkmcnt(1)
	v_mfma_f32_32x32x16_bf16 v[48:63], v[128:131], v[232:235], v[48:63]
	ds_read_b128 v[128:131], v201 offset:30304
	ds_read_b128 v[200:203], v247
	ds_read_b128 v[196:199], v247 offset:512
	ds_read_b128 v[192:195], v248
	ds_read_b128 v[188:191], v248 offset:512
	v_exp_f32_e32 v72, v72
	v_exp_f32_e32 v73, v73
	v_add_f32_e32 v212, v70, v212
	v_add_f32_e32 v212, v71, v212
	v_mfma_f32_32x32x16_bf16 v[32:47], v[132:135], v[232:235], v[32:47]
	v_exp_f32_e32 v74, v74
	v_exp_f32_e32 v75, v75
	v_add_f32_e32 v212, v72, v212
	v_add_f32_e32 v212, v73, v212
	s_waitcnt lgkmcnt(4)
	v_mfma_f32_32x32x16_bf16 v[16:31], v[136:139], v[232:235], v[16:31]
	v_exp_f32_e32 v76, v76
	v_exp_f32_e32 v77, v77
	v_add_f32_e32 v212, v74, v212
	v_add_f32_e32 v212, v75, v212
	v_mfma_f32_32x32x16_bf16 v[0:15], v[128:131], v[232:235], v[0:15]
	v_exp_f32_e32 v78, v78
	v_exp_f32_e32 v79, v79
	v_add_f32_e32 v212, v76, v212
	v_add_f32_e32 v212, v77, v212
	s_min_u32 s12, s34, 0x7f
	s_lshl_b32 s12, s12, 6
	s_sub_i32 s14, s12, s47
	s_sub_i32 s15, s14, 31
	s_cmpk_lt_i32 s15, 0x22f
	s_cselect_b32 s98, s100, s101
	s_cselect_b32 s15, 1, 0
	s_cmpk_gt_i32 s14, 0xfd92
	s_cselect_b32 s15, s15, 0
	s_cmp_lg_u32 s15, 0
	s_cbranch_scc1 .Lgather_o
	s_cmp_lg_u32 s99, s98
	s_cbranch_scc1 .Lz_upd_o

; #define FLAS __attribute__((address_space(3)))
; #define FA_SB() __builtin_amdgcn_sched_barrier(0)
; #define FA_EXP2(J, PX, R) do { const float e0_ = __builtin_amdgcn_exp2f(PX[R]), e1_ = __builtin_amdgcn_exp2f(PX[(R) + 1]); ps += e0_; ps += e1_; PWN[(J) >> 2][(J) & 3] = cvtpk(e0_, e1_); } while (0)
; __device__ __forceinline__ void attn_unit_a(FLAS unsigned char* lds, const Unit u) {
;     ...
;         kf[0] = FA_KF(2, 0); kf[1] = FA_KF(2, 1); FA_EXP2(9, pC1, 2); FA_SB();
;         pN0 = __builtin_amdgcn_mfma_f32_32x32x16_bf16(kf[2], qr[1], pN0, 0, 0, 0); FA_EXP2(10, pC1, 4); FA_SB();
;         pN1 = __builtin_amdgcn_mfma_f32_32x32x16_bf16(kf[3], qr[1], pN1, 0, 0, 0); kf[2] = FA_KF(3, 0); kf[3] = FA_KF(3, 1); FA_EXP2(11, pC1, 6); FA_SB();
;         pN0 = __builtin_amdgcn_mfma_f32_32x32x16_bf16(kf[0], qr[2], pN0, 0, 0, 0); FA_EXP2(12, pC1, 8); FA_SB();
;         pN1 = __builtin_amdgcn_mfma_f32_32x32x16_bf16(kf[1], qr[2], pN1, 0, 0, 0); FA_EXP2(13, pC1, 10); FA_SB();
;         pN0 = __builtin_amdgcn_mfma_f32_32x32x16_bf16(kf[2], qr[3], pN0, 0, 0, 0); FA_EXP2(14, pC1, 12); FA_SB();
;         pN1 = __builtin_amdgcn_mfma_f32_32x32x16_bf16(kf[3], qr[3], pN1, 0, 0, 0); FA_EXP2(15, pC1, 14); FA_SB();
;     ...
;         lsum += ps; cbC = cbN;
;         if (i + 2 < NT) { *(FLAS u32x4*)(lds + LA_K + (i & 1) * KBUF + kdst) = kreg;
; #pragma unroll
;             for (int j = 0; j < 2; ++j) { *(FLAS u32x2*)(lds + LA_V + ((i + 2) & 3) * VBUF + vdst + j * 64 * VPITCH) = (u32x2){vreg[j].x, vreg[j].y}; *(FLAS u32x2*)(lds + LA_V + ((i + 2) & 3) * VBUF + vdst + j * 64 * VPITCH + 16) = (u32x2){vreg[j].z, vreg[j].w}; } }
.Lk2_o:
	ds_read_b128 v[128:131], v249
	ds_read_b128 v[132:135], v249 offset:512
	v_mfma_f32_32x32x16_bf16 v[96:111], v[192:195], v[164:167], v[96:111]
	v_exp_f32_e32 v84, v84
	v_exp_f32_e32 v85, v85
	v_mfma_f32_32x32x16_bf16 v[112:127], v[188:191], v[164:167], v[112:127]
	ds_read_b128 v[136:139], v250
	ds_read_b128 v[140:143], v250 offset:512
	v_add_u32_e32 v204, s18, v245
	v_add_u32_e32 v205, 0x4000, v204
	v_add_u32_e32 v204, 0x6000, v204
	s_waitcnt vmcnt(2)
	ds_write_b128 v225, v[176:179] offset:8192
	s_waitcnt vmcnt(1)
	ds_write2_b64 v205, v[180:181], v[182:183] offset1:2
	s_waitcnt vmcnt(0)
	ds_write2_b64 v204, v[184:185], v[186:187] offset0:128 offset1:130
	v_exp_f32_e32 v86, v86
	v_exp_f32_e32 v87, v87
	s_add_i32 s12, s34, -1
	s_and_b32 s18, s12, 3
	s_mulk_i32 s18, 0x4800
	v_add_u32_e32 v200, s18, v251
	s_waitcnt lgkmcnt(5)
	v_mfma_f32_32x32x16_bf16 v[96:111], v[128:131], v[168:171], v[96:111]
	ds_read_b128 v[128:131], v200 offset:16384
	v_exp_f32_e32 v88, v88
	v_exp_f32_e32 v89, v89
	v_mfma_f32_32x32x16_bf16 v[112:127], v[132:135], v[168:171], v[112:127]
	ds_read_b128 v[132:135], v200 offset:20992
	v_exp_f32_e32 v90, v90
	v_exp_f32_e32 v91, v91
	s_waitcnt lgkmcnt(5)
	v_mfma_f32_32x32x16_bf16 v[96:111], v[136:139], v[172:175], v[96:111]
	ds_read_b128 v[136:139], v200 offset:25600
	v_exp_f32_e32 v92, v92
	v_exp_f32_e32 v93, v93
	v_mfma_f32_32x32x16_bf16 v[112:127], v[140:143], v[172:175], v[112:127]
	v_exp_f32_e32 v94, v94
	v_exp_f32_e32 v95, v95
